# differential-combine loop software-pipelined by one trip (next trip's loads issued after this trip's data is copied out, counted vmcnt(1))
# speedup vs baseline: 1.0189x; 1.0031x over previous
; __device__ __forceinline__ int opaque_tid() { int t = threadIdx.x; asm volatile("" : "+v"(t)); return t; }
; #define ARGS() (*opaque_kargs())
; #define WSPTR() ({ unsigned char* w_ = ARGS().ws; asm volatile("" : "+s"(w_)); w_; })
; #define G opaque_s(G0)
; #define bx opaque_s(bx0)
; __global__ void __launch_bounds__(NWAVES * 64, 2) mega_fwd(Args args_) {
;     ...
;             { unsigned char* ws = WSPTR(); const int l = step / 3;
;               const int tid = opaque_tid(), lane = tid & 63, wave = __builtin_amdgcn_readfirstlane(tid >> 6);
;               const int gw = bx * NWAVES + wave, NGW = G * NWAVES;
;               const bf16* OB = (const bf16*)(ws + WS_OB); bf16* OC = (bf16*)(ws + WS_OCN);
;               const float lam_init = l == 0 ? 0.2f : 0.35550907f;
;               const float s1 = wave_sum(ARGS().in[14][l * 64 + lane] * ARGS().in[15][l * 64 + lane]), s2 = wave_sum(ARGS().in[16][l * 64 + lane] * ARGS().in[17][l * 64 + lane]);
;               const float lam = expf(s1) - expf(s2) + lam_init;
;               const int h = lane >> 4, c0 = (lane & 15) * 8;
;               f32x4 sg0 = *(const f32x4*)(ARGS().in[18] + l * 128 + c0), sg1 = *(const f32x4*)(ARGS().in[18] + l * 128 + c0 + 4);
;               sg0 = sg0 * (1.0f - lam_init); sg1 = sg1 * (1.0f - lam_init);
;               for (int m = gw; m < M; m += NGW) {
.LBB0_1361:
	s_mov_b64 s[0:1], s[84:85]
	s_load_dwordx2 s[4:5], s[0:1], 0xe0
	v_mov_b32_e32 v8, v230
	s_mov_b32 s0, s76
	s_mov_b32 s1, s86
	s_mov_b64 s[2:3], s[84:85]
	s_waitcnt lgkmcnt(0)
	s_load_dwordx2 s[2:3], s[2:3], 0x70
	v_and_b32_e32 v9, 63, v8
	v_readlane_b32 s6, v254, 45
	s_lshl_b32 s0, s0, 3
	v_and_b32_e32 v11, 64, v236
	v_or_b32_e32 v0, s6, v9
	v_lshlrev_b32_e32 v0, 2, v0
	s_waitcnt lgkmcnt(0)
	global_load_dword v5, v0, s[2:3]
	s_mov_b64 s[2:3], s[84:85]
	s_load_dwordx2 s[2:3], s[2:3], 0x78
	s_mov_b64 s[6:7], s[84:85]
	v_xor_b32_e32 v12, 1, v236
	v_add_u32_e32 v11, 64, v11
	v_cmp_lt_i32_e32 vcc, v12, v11
	s_waitcnt lgkmcnt(0)
	global_load_dword v6, v0, s[2:3]
	s_mov_b64 s[2:3], s[84:85]
	s_load_dwordx2 s[2:3], s[2:3], 0x80
	v_cndmask_b32_e32 v12, v236, v12, vcc
	v_lshlrev_b32_e32 v24, 2, v12
	v_xor_b32_e32 v13, 2, v236
	v_cmp_lt_i32_e32 vcc, v13, v11
	s_waitcnt lgkmcnt(0)
	global_load_dword v7, v0, s[2:3]
	s_load_dwordx2 s[2:3], s[6:7], 0x88
	v_readfirstlane_b32 s6, v8
	s_ashr_i32 s6, s6, 6
	s_add_i32 s0, s0, s6
	v_readlane_b32 s6, v254, 15
	s_waitcnt lgkmcnt(0)
	global_load_dword v10, v0, s[2:3]
	s_mov_b64 s[2:3], s[84:85]
	s_load_dwordx2 s[2:3], s[2:3], 0x90
	v_readlane_b32 s7, v254, 16
	s_and_b64 s[6:7], s[6:7], exec
	s_cselect_b32 s6, 0x80, 0
	v_lshlrev_b32_e32 v0, 3, v8
	s_lshl_b32 s6, s6, 2
	v_and_b32_e32 v0, 0x78, v0
	s_waitcnt lgkmcnt(0)
	s_add_u32 s2, s2, s6
	v_lshlrev_b32_e32 v4, 2, v0
	s_addc_u32 s3, s3, 0
	global_load_dwordx4 v[0:3], v4, s[2:3]
	v_cndmask_b32_e32 v13, v236, v13, vcc
	v_lshlrev_b32_e32 v25, 2, v13
	v_xor_b32_e32 v14, 4, v236
	v_cmp_lt_i32_e32 vcc, v14, v11
	s_mov_b64 s[2:3], s[84:85]
	s_cmpk_gt_i32 s0, 0x3fff
	v_cndmask_b32_e32 v13, v236, v14, vcc
	v_lshlrev_b32_e32 v26, 2, v13
	s_waitcnt vmcnt(0)
	v_mul_f32_e32 v12, v5, v6
	ds_bpermute_b32 v12, v24, v12
	s_waitcnt lgkmcnt(0)
	v_fmac_f32_e32 v12, v5, v6
	ds_bpermute_b32 v5, v25, v12
	v_xor_b32_e32 v6, 8, v236
	v_cmp_lt_i32_e32 vcc, v6, v11
	s_waitcnt lgkmcnt(0)
	v_add_f32_e32 v5, v12, v5
	ds_bpermute_b32 v13, v26, v5
	v_cndmask_b32_e32 v6, v236, v6, vcc
	v_mul_f32_e32 v12, v7, v10
	ds_bpermute_b32 v12, v24, v12
	v_lshlrev_b32_e32 v27, 2, v6
	s_waitcnt lgkmcnt(1)
	v_add_f32_e32 v5, v5, v13
	ds_bpermute_b32 v6, v27, v5
	s_waitcnt lgkmcnt(1)
	v_fmac_f32_e32 v12, v7, v10
	ds_bpermute_b32 v7, v25, v12
	v_xor_b32_e32 v10, 16, v236
	s_waitcnt lgkmcnt(1)
	v_add_f32_e32 v5, v5, v6
	v_cmp_lt_i32_e32 vcc, v10, v11
	s_waitcnt lgkmcnt(0)
	v_add_f32_e32 v6, v12, v7
	ds_bpermute_b32 v7, v26, v6
	v_cndmask_b32_e32 v10, v236, v10, vcc
	v_lshlrev_b32_e32 v143, 2, v10
	ds_bpermute_b32 v10, v143, v5
	s_waitcnt lgkmcnt(1)
	v_add_f32_e32 v6, v6, v7
	ds_bpermute_b32 v7, v27, v6
	s_waitcnt lgkmcnt(1)
	v_add_f32_e32 v12, v5, v10
	v_xor_b32_e32 v5, 32, v236
	v_cmp_lt_i32_e32 vcc, v5, v11
	s_waitcnt lgkmcnt(0)
	v_add_f32_e32 v6, v6, v7
	ds_bpermute_b32 v7, v143, v6
	v_cndmask_b32_e32 v5, v236, v5, vcc
	v_lshlrev_b32_e32 v142, 2, v5
	ds_bpermute_b32 v13, v142, v12
	s_waitcnt lgkmcnt(1)
	v_add_f32_e32 v10, v6, v7
	ds_bpermute_b32 v11, v142, v10
	s_cbranch_scc1 .LBB0_1364
	s_load_dwordx2 s[8:9], s[2:3], 0x90
	s_lshl_b32 s2, s1, 3
	v_mov_b32_e32 v14, 0x3eb60549
	v_mov_b32_e32 v15, 0x3e4ccccd
	s_waitcnt lgkmcnt(0)
	v_add_f32_e32 v19, v12, v13
	s_add_u32 s6, s8, s6
	s_addc_u32 s7, s9, 0
	global_load_dwordx4 v[4:7], v4, s[6:7] offset:16
	v_readlane_b32 s6, v254, 35
	v_readlane_b32 s7, v254, 36
	v_add_f32_e32 v10, v10, v11
	v_lshlrev_b32_e32 v9, 4, v9
	v_cndmask_b32_e64 v18, v14, v15, s[6:7]
	s_mul_i32 s6, s1, 0x6000
	v_mul_f32_e32 v14, 0x3fb8aa3b, v19
	s_mov_b32 s1, 0x3fb8aa3b
	v_mul_f32_e32 v15, 0x3fb8aa3b, v10
	v_fma_f32 v16, v19, s1, -v14
	v_rndne_f32_e32 v17, v14
	v_fma_f32 v20, v10, s1, -v15
	v_rndne_f32_e32 v21, v15
	v_fmac_f32_e32 v16, 0x32a5705f, v19
	v_sub_f32_e32 v14, v14, v17
	v_and_b32_e32 v12, 48, v8
	v_fmac_f32_e32 v20, 0x32a5705f, v10
	v_sub_f32_e32 v15, v15, v21
	v_add_f32_e32 v14, v14, v16
	v_lshlrev_b32_e32 v11, 4, v8
	v_sub_f32_e32 v8, 1.0, v18
	v_and_b32_e32 v9, 0x300, v9
	v_lshlrev_b32_e32 v112, 5, v12
	v_cvt_i32_f32_e32 v17, v17
	v_add_f32_e32 v15, v15, v20
	v_exp_f32_e32 v16, v14
	v_and_b32_e32 v11, 0xf0, v11
	v_pk_mul_f32 v[12:13], v[8:9], v[2:3] op_sel_hi:[0,1]
	v_mad_i64_i32 v[2:3], s[12:13], s0, v241, v[112:113]
	v_cvt_i32_f32_e32 v21, v21
	v_exp_f32_e32 v20, v15
	v_or_b32_e32 v2, v2, v11
	s_ashr_i32 s1, s0, 31
	s_mov_b64 s[8:9], 0xb400500
	v_lshl_add_u64 v[2:3], s[4:5], 0, v[2:3]
	s_lshl_b64 s[12:13], s[0:1], 10
	s_mov_b32 s1, 0xc2ce8ed0
	v_pk_mul_f32 v[0:1], v[8:9], v[0:1] op_sel_hi:[0,1]
	v_lshl_add_u64 v[14:15], v[2:3], 0, s[8:9]
	v_or3_b32 v2, s12, v9, v11
	v_mov_b32_e32 v3, s13
	v_ldexp_f32 v9, v16, v17
	v_cmp_ngt_f32_e32 vcc, s1, v19
	s_mov_b64 s[10:11], 0x9c00000
	v_ldexp_f32 v11, v20, v21
	v_lshl_add_u64 v[2:3], s[4:5], 0, v[2:3]
	v_cndmask_b32_e32 v9, 0, v9, vcc
	v_cmp_ngt_f32_e32 vcc, s1, v10
	s_mov_b32 s1, 0x42b17218
	v_lshl_add_u64 v[16:17], v[2:3], 0, s[10:11]
	v_cndmask_b32_e32 v11, 0, v11, vcc
	v_cmp_nlt_f32_e32 vcc, s1, v19
	v_mov_b32_e32 v3, 0x7f800000
	s_ashr_i32 s3, s2, 31
	v_cndmask_b32_e32 v2, v3, v9, vcc
	v_cmp_nlt_f32_e32 vcc, s1, v10
	s_lshl_b64 s[8:9], s[2:3], 10
	s_mul_hi_i32 s7, s2, 0xc00
	v_cndmask_b32_e32 v3, v3, v11, vcc
	v_sub_f32_e32 v2, v2, v3
	v_add_f32_e32 v18, v18, v2
	v_mov_b32_e32 v19, v18
	v_mov_b32_e32 v2, v18
	v_mov_b32_e32 v3, v18
	s_waitcnt vmcnt(0)
	v_pk_mul_f32 v[20:21], v[8:9], v[4:5] op_sel_hi:[0,1]
	v_pk_mul_f32 v[22:23], v[8:9], v[6:7] op_sel_hi:[0,1]
	v_mbcnt_lo_u32_b32 v38, -1, 0
	v_mbcnt_hi_u32_b32 v38, -1, v38
	v_lshrrev_b32_e32 v38, 4, v38
	s_lshl_b32 s24, s0, 5
	s_add_i32 s24, s24, 0xf600000
	s_lshl_b32 s25, s0, 6
	s_add_i32 s25, s25, 0xf700000
	v_lshl_add_u32 v39, v38, 4, s25
	v_lshl_add_u32 v38, v38, 3, s24
	s_lshl_b32 s12, s2, 5
	s_lshl_b32 s13, s2, 6
	s_bitcmp1_b32 s32, 0
	s_cselect_b64 s[14:15], -1, 0
	v_add_co_u32_e32 v46, vcc, 0xffffff00, v14
	s_nop 1
	v_addc_co_u32_e32 v47, vcc, -1, v15, vcc
	global_load_dwordx4 v[48:51], v[46:47], off
	global_load_dwordx4 v[52:55], v[14:15], off
	global_load_dwordx2 v[56:57], v38, s[4:5]
	global_load_dwordx4 v[58:61], v39, s[4:5]
	v_lshl_add_u64 v[14:15], v[14:15], 0, s[6:7]
	v_add_u32_e32 v38, s12, v38
	v_add_u32_e32 v39, s13, v39
	s_waitcnt vmcnt(0)
; __device__ __forceinline__ u32x4 pack8(const f32x4 a, const f32x4 b) { u32x4 w; w.x = cvt_pk_bf16(a[0], a[1]); w.y = cvt_pk_bf16(a[2], a[3]); w.z = cvt_pk_bf16(b[0], b[1]); w.w = cvt_pk_bf16(b[2], b[3]); return w; }
; __global__ void __launch_bounds__(NWAVES * 64, 2) mega_fwd(Args args_) {
;     ...
;               for (int m = gw; m < M; m += NGW) {
;                   const bf16* op = OB + (size_t)m * OPW + 512 + 256 * h + c0;
;                   f32x4 a0, a1, b0, b1; pg8::unpack8(*(const v4u*)op, a0, a1); pg8::unpack8(*(const v4u*)(op + 128), b0, b1);
;                   a0 = a0 - b0 * lam; a1 = a1 - b1 * lam;
;                   float ss = (a0[0] * a0[0] + a0[1] * a0[1]) + (a0[2] * a0[2] + a0[3] * a0[3]) + (a1[0] * a1[0] + a1[1] * a1[1]) + (a1[2] * a1[2] + a1[3] * a1[3]);
;                   ss += __shfl_xor(ss, 1); ss += __shfl_xor(ss, 2); ss += __shfl_xor(ss, 4); ss += __shfl_xor(ss, 8);
;                   const float rn = __builtin_amdgcn_rsqf(ss * (1.0f / 128.0f) + 1e-6f);
;                   *(v4u*)(OC + (size_t)m * 512 + 128 * h + c0) = pg8::pack8(a0 * rn * sg0, a1 * rn * sg1);
.LBB0_1363:
	s_waitcnt vmcnt(1)
	v_mov_b64_e32 v[4:5], v[48:49]
	v_mov_b64_e32 v[6:7], v[50:51]
	v_mov_b64_e32 v[8:9], v[52:53]
	v_mov_b64_e32 v[10:11], v[54:55]
	v_mov_b64_e32 v[40:41], v[56:57]
	v_mov_b64_e32 v[42:43], v[58:59]
	v_mov_b64_e32 v[44:45], v[60:61]
	v_add_co_u32_e32 v46, vcc, 0xffffff00, v14
	s_nop 1
	v_addc_co_u32_e32 v47, vcc, -1, v15, vcc
	global_load_dwordx4 v[48:51], v[46:47], off
	global_load_dwordx4 v[52:55], v[14:15], off
	global_load_dwordx2 v[56:57], v38, s[4:5]
	global_load_dwordx4 v[58:61], v39, s[4:5]
	v_lshl_add_u64 v[14:15], v[14:15], 0, s[6:7]
	v_add_u32_e32 v38, s12, v38
	v_add_u32_e32 v39, s13, v39
	v_xor_b32_e32 v29, 0x80000000, v3
	v_xor_b32_e32 v28, 0x80000000, v2
	s_add_i32 s0, s0, s2
	s_cmpk_gt_i32 s0, 0x3fff
	v_lshlrev_b32_e32 v30, 16, v4
	v_and_b32_e32 v31, 0xffff0000, v4
	v_lshlrev_b32_e32 v4, 16, v5
	v_and_b32_e32 v5, 0xffff0000, v5
	v_lshlrev_b32_e32 v34, 16, v8
	v_and_b32_e32 v35, 0xffff0000, v8
	v_lshlrev_b32_e32 v8, 16, v9
	v_and_b32_e32 v9, 0xffff0000, v9
	v_lshlrev_b32_e32 v32, 16, v6
	v_and_b32_e32 v33, 0xffff0000, v6
	v_lshlrev_b32_e32 v6, 16, v7
	v_and_b32_e32 v7, 0xffff0000, v7
	v_lshlrev_b32_e32 v36, 16, v10
	v_and_b32_e32 v37, 0xffff0000, v10
	v_lshlrev_b32_e32 v10, 16, v11
	v_and_b32_e32 v11, 0xffff0000, v11
	v_add_f32_e32 v40, v40, v42
	v_add_f32_e32 v41, v41, v44
	v_add_f32_e32 v40, v40, v43
	v_add_f32_e32 v41, v41, v45
	v_rcp_f32_e32 v40, v40
	v_rcp_f32_e32 v41, v41
	s_nop 0
	v_cndmask_b32_e64 v40, 1.0, v40, s[14:15]
	v_cndmask_b32_e64 v41, 1.0, v41, s[14:15]
	v_mul_f32_e32 v30, v30, v40
	v_mul_f32_e32 v31, v31, v40
	v_mul_f32_e32 v4, v4, v40
	v_mul_f32_e32 v5, v5, v40
	v_mul_f32_e32 v32, v32, v40
	v_mul_f32_e32 v33, v33, v40
	v_mul_f32_e32 v6, v6, v40
	v_mul_f32_e32 v7, v7, v40
	v_mul_f32_e32 v34, v34, v41
	v_mul_f32_e32 v35, v35, v41
	v_mul_f32_e32 v8, v8, v41
	v_mul_f32_e32 v9, v9, v41
	v_mul_f32_e32 v36, v36, v41
	v_mul_f32_e32 v37, v37, v41
	v_mul_f32_e32 v10, v10, v41
	v_mul_f32_e32 v11, v11, v41
	v_pk_fma_f32 v[30:31], v[18:19], v[34:35], v[30:31] neg_lo:[1,0,0] neg_hi:[1,0,0]
	v_pk_fma_f32 v[4:5], v[28:29], v[8:9], v[4:5]
	v_pk_fma_f32 v[8:9], v[18:19], v[36:37], v[32:33] neg_lo:[1,0,0] neg_hi:[1,0,0]
	v_pk_fma_f32 v[6:7], v[28:29], v[10:11], v[6:7]
	v_pk_mul_f32 v[10:11], v[4:5], v[4:5]
	v_pk_mul_f32 v[28:29], v[30:31], v[30:31]
	v_pk_mul_f32 v[32:33], v[6:7], v[6:7]
	v_pk_mul_f32 v[34:35], v[8:9], v[8:9]
	v_pk_mov_b32 v[36:37], v[28:29], v[10:11] op_sel:[1,0]
	v_mov_b32_e32 v29, v11
	v_mov_b32_e32 v10, v32
	v_mov_b32_e32 v11, v34
	v_mov_b32_e32 v34, v33
	v_pk_add_f32 v[28:29], v[36:37], v[28:29]
	v_pk_add_f32 v[10:11], v[10:11], v[34:35]
	v_add_f32_e32 v28, v28, v29
	v_add_f32_e32 v11, v11, v28
	v_add_f32_e32 v10, v10, v11
	ds_bpermute_b32 v11, v24, v10
	s_waitcnt lgkmcnt(0)
	v_add_f32_e32 v10, v10, v11
	ds_bpermute_b32 v11, v25, v10
	s_waitcnt lgkmcnt(0)
	v_add_f32_e32 v10, v10, v11
	ds_bpermute_b32 v11, v26, v10
	s_waitcnt lgkmcnt(0)
	v_add_f32_e32 v10, v10, v11
	ds_bpermute_b32 v11, v27, v10
	s_waitcnt lgkmcnt(0)
	v_add_f32_e32 v10, v10, v11
	v_fmamk_f32 v10, v10, 0x3c000000, v231
	v_rsq_f32_e32 v10, v10
	s_nop 0
	v_pk_mul_f32 v[28:29], v[30:31], v[10:11] op_sel_hi:[1,0]
	v_pk_mul_f32 v[4:5], v[4:5], v[10:11] op_sel_hi:[1,0]
	v_pk_mul_f32 v[8:9], v[8:9], v[10:11] op_sel_hi:[1,0]
	v_pk_mul_f32 v[6:7], v[6:7], v[10:11] op_sel_hi:[1,0]
	v_pk_mul_f32 v[10:11], v[12:13], v[4:5]
	v_pk_mul_f32 v[4:5], v[0:1], v[28:29]
	v_pk_mul_f32 v[28:29], v[22:23], v[6:7]
	v_pk_mul_f32 v[6:7], v[20:21], v[8:9]
	v_cvt_pk_bf16_f32 v4, v4, v5
	v_cvt_pk_bf16_f32 v5, v10, v11
	v_cvt_pk_bf16_f32 v6, v6, v7
	v_cvt_pk_bf16_f32 v7, v28, v29
	global_store_dwordx4 v[16:17], v[4:7], off
	v_lshl_add_u64 v[16:17], v[16:17], 0, s[8:9]
	s_cbranch_scc0 .LBB0_1363
